# P0 by wave role: odd waves run KV shift + row pass first and their transposes afterwards, even waves keep the original order
# speedup vs baseline: 1.0018x; 1.0018x over previous
.LBB0_5:
	s_or_b64 exec, exec, s[4:5]
	v_mov_b32_e32 v3, v228
	s_load_dwordx2 s[8:9], s[0:1], 0xc0
	s_load_dwordx16 s[36:51], s[0:1], 0x0
	v_readfirstlane_b32 s5, v3
	v_readlane_b32 s4, v254, 0
	s_ashr_i32 s6, s5, 6
	s_lshl_b32 s4, s4, 3
	v_and_b32_e32 v2, 63, v3
	v_writelane_b32 v254, s4, 5
	s_add_i32 s4, s6, s4
	s_waitcnt lgkmcnt(0)
	s_lshl_b32 s14, s8, 3
	s_cmpk_gt_i32 s4, 0x1cff
	v_lshlrev_b32_e32 v34, 3, v2
	v_writelane_b32 v254, s14, 6
	s_mov_b32 s100, 0
	s_cbranch_scc1 .LBB0_24
	s_bitcmp1_b32 s6, 0
	s_cbranch_scc0 .Lp0_bb6
	s_mov_b32 s100, 1
	s_branch .LBB0_24
.Lp0_bb6:
	s_lshl_b32 s6, s6, 14
	v_lshrrev_b32_e32 v35, 3, v2
	v_and_b32_e32 v14, 56, v34
	s_add_i32 s6, s6, 0
	v_lshrrev_b32_e32 v1, 5, v2
	v_lshlrev_b32_e32 v3, 2, v3
	v_mul_u32_u24_e32 v5, 0x84, v14
	v_lshlrev_b32_e32 v6, 2, v35
	v_and_b32_e32 v4, 0x7c, v3
	v_mul_u32_u24_e32 v3, 0x84, v1
	v_add3_u32 v58, s6, v5, v6
	v_mov_b32_e32 v5, 0
	v_add3_u32 v3, s6, v4, v3
	v_lshl_add_u64 v[6:7], s[70:71], 0, v[4:5]
	v_lshl_add_u64 v[8:9], s[68:69], 0, v[4:5]
	v_lshl_add_u64 v[10:11], s[50:51], 0, v[4:5]
	v_lshl_add_u64 v[12:13], s[48:49], 0, v[4:5]
	v_lshlrev_b32_e32 v4, 1, v14
	v_lshl_add_u64 v[20:21], s[82:83], 0, v[4:5]
	s_mov_b64 s[8:9], 0x1580000
	s_cmp_lg_u64 s[76:77], 0
	s_mov_b64 s[10:11], 0xd80000
	v_lshl_add_u64 v[14:15], v[20:21], 0, s[8:9]
	s_cselect_b64 s[8:9], -1, 0
	v_lshl_add_u64 v[16:17], v[20:21], 0, s[10:11]
	s_mov_b64 s[10:11], 0xb80000
	s_cmp_lg_u64 s[72:73], 0
	v_lshl_add_u64 v[18:19], v[20:21], 0, s[10:11]
	s_cselect_b64 s[10:11], -1, 0
	s_mov_b64 s[12:13], 0x80000
	s_lshl_b32 s6, s4, 1
	s_mov_b32 s7, 0
	v_or_b32_e32 v59, 8, v35
	v_or_b32_e32 v60, 16, v35
	v_or_b32_e32 v61, 24, v35
	v_lshl_add_u64 v[20:21], v[20:21], 0, s[12:13]
	s_lshl_b32 s16, s4, 5
	s_lshl_b32 s17, s14, 5
	s_add_i32 s18, s6, 0x1d600
	s_lshl_b32 s19, s14, 1
	s_movk_i32 s20, 0x5800
	v_add_u32_e32 v62, 0x400, v3
	v_add_u32_e32 v63, 0x800, v3
	v_add_u32_e32 v64, 0xc00, v3
	v_add_u32_e32 v65, 0x1000, v3
	v_add_u32_e32 v66, 0x1400, v3
	v_add_u32_e32 v67, 0x1800, v3
	v_add_u32_e32 v68, 0x1c00, v3
	s_mov_b32 s21, s4
	s_branch .LBB0_9

.LBB0_24:
	s_cmp_eq_u32 s100, 2
	s_cbranch_scc1 .Lp0_done
	v_lshl_or_b32 v1, s4, 6, v2
	s_mov_b32 s6, 0xfe000
	v_cmp_gt_i32_e32 vcc, s6, v1
	s_and_saveexec_b64 s[8:9], vcc
	v_writelane_b32 v254, s36, 7
	s_load_dwordx2 s[52:53], s[0:1], 0xc0
	s_nop 0
	v_writelane_b32 v254, s37, 8
	v_writelane_b32 v254, s38, 9
	v_writelane_b32 v254, s39, 10
	v_writelane_b32 v254, s40, 11
	v_writelane_b32 v254, s41, 12
	v_writelane_b32 v254, s42, 13
	v_writelane_b32 v254, s43, 14
	v_writelane_b32 v254, s44, 15
	v_writelane_b32 v254, s45, 16
	v_writelane_b32 v254, s46, 17
	v_writelane_b32 v254, s47, 18
	v_writelane_b32 v254, s48, 19
	v_writelane_b32 v254, s49, 20
	v_writelane_b32 v254, s50, 21
	v_writelane_b32 v254, s51, 22
	s_nop 0
	v_readlane_b32 s50, v254, 0
	s_cbranch_execz .LBB0_32
	s_add_u32 s10, s80, 0x84c0000
	s_addc_u32 s11, s81, 0
	s_add_u32 s12, s80, 0x94c0000
	s_addc_u32 s13, s81, 0
	s_waitcnt lgkmcnt(0)
	s_lshl_b32 s16, s52, 9
	v_cvt_f32_u32_e32 v3, s16
	s_add_i32 s7, s50, s52
	s_lshl_b32 s7, s7, 9
	s_andn2_b32 s5, s5, 63
	v_rcp_iflag_f32_e32 v3, v3
	s_add_i32 s7, s7, s5
	v_or_b32_e32 v4, s7, v2
	v_cmp_gt_i32_e32 vcc, s6, v4
	v_mul_f32_e32 v3, 0x4f7ffffe, v3
	v_cvt_u32_f32_e32 v3, v3
	v_max_i32_e32 v5, 0xfe000, v4
	v_addc_co_u32_e64 v4, s[6:7], 0, v4, vcc
	s_sub_i32 s5, 0, s16
	v_sub_u32_e32 v4, v5, v4
	v_mul_lo_u32 v5, s5, v3
	v_mul_hi_u32 v5, v3, v5
	v_add_u32_e32 v3, v3, v5
	v_mul_hi_u32 v3, v4, v3
	v_mul_lo_u32 v5, v3, s16
	v_sub_u32_e32 v4, v4, v5
	v_add_u32_e32 v5, 1, v3
	v_cmp_le_u32_e64 s[6:7], s16, v4
	s_nop 1
	v_cndmask_b32_e64 v3, v3, v5, s[6:7]
	v_subrev_u32_e32 v5, s16, v4
	v_cndmask_b32_e64 v4, v4, v5, s[6:7]
	v_add_u32_e32 v5, 1, v3
	v_cmp_le_u32_e64 s[6:7], s16, v4
	s_nop 1
	v_cndmask_b32_e64 v3, v3, v5, s[6:7]
	v_addc_co_u32_e32 v3, vcc, 0, v3, vcc
	v_and_b32_e32 v4, 3, v3
	v_cmp_ne_u32_e32 vcc, 3, v4
	s_and_saveexec_b64 s[6:7], vcc
	s_cbranch_execz .LBB0_29
	s_load_dwordx16 s[56:71], s[0:1], 0x0
	v_add_u32_e32 v4, 1, v3
	v_and_b32_e32 v4, 3, v4
	s_mov_b64 s[14:15], 0
	s_mov_b32 s5, 0x81020409
	s_waitcnt lgkmcnt(0)
	s_mov_b64 s[36:37], s[56:57]
	s_movk_i32 s17, 0xe040
	s_mov_b64 s[40:41], s[60:61]
	s_mov_b64 s[42:43], s[62:63]
	s_mov_b64 s[38:39], s[58:59]
	s_mov_b64 s[44:45], s[64:65]
	s_mov_b64 s[46:47], s[66:67]

.Lp0_tr2:
	s_mov_b32 s100, 2
	s_sub_u32 s0, s2, 0xc0
	s_subb_u32 s1, s3, 0
	s_load_dwordx4 s[48:51], s[0:1], 0x30
	s_load_dwordx4 s[68:71], s[0:1], 0x80
	v_readfirstlane_b32 s5, v228
	v_readlane_b32 s4, v254, 5
	v_readlane_b32 s14, v254, 6
	v_and_b32_e32 v2, 63, v228
	v_mov_b32_e32 v3, v228
	s_ashr_i32 s6, s5, 6
	s_add_i32 s4, s6, s4
	v_lshlrev_b32_e32 v34, 3, v2
	s_waitcnt lgkmcnt(0)
	s_cmpk_gt_i32 s4, 0x1cff
	s_cbranch_scc1 .Lp0_done
	s_branch .Lp0_bb6
.Lp0_done:
	v_readlane_b32 s50, v254, 0
	v_readlane_b32 s51, v254, 22
	s_branch .Lp0_end
.LBB0_58:
	s_cmp_eq_u32 s100, 1
	s_cbranch_scc1 .Lp0_tr2
